# job1 QK: K fragment LDS reads issued three k-steps ahead (rolling) instead of all twelve up front
# speedup vs baseline: 1.0111x; 1.0042x over previous
.LBB0_1165:
	s_sub_i32 s45, s42, 64
	s_cmp_ge_u32 s45, s66
	s_cselect_b64 s[48:49], -1, 0
	s_cmp_gt_i32 s44, s39
	s_cselect_b64 s[50:51], -1, 0
	s_or_b64 s[48:49], s[50:51], s[48:49]
	s_and_b64 vcc, exec, s[48:49]
	s_cbranch_vccnz .LBB0_1169
	v_add_u32_e32 v120, v124, v198
	ds_read_b128 v[136:139], v120
	ds_read_b128 v[140:143], v120 offset:6656
	ds_read_b128 v[144:147], v120 offset:32
	ds_read_b128 v[148:151], v120 offset:6688
	ds_read_b128 v[152:155], v120 offset:64
	ds_read_b128 v[156:159], v120 offset:6720
	v_add_u32_e32 v184, v125, v126
	s_waitcnt lgkmcnt(5)
	v_mfma_f32_32x32x16_bf16 v[34:49], v[136:139], v[66:69], v[220:235]
	s_waitcnt lgkmcnt(4)
	v_mfma_f32_32x32x16_bf16 v[50:65], v[140:143], v[66:69], v[220:235]
	ds_read_b128 v[160:163], v120 offset:96
	ds_read_b128 v[164:167], v120 offset:6752
	s_waitcnt lgkmcnt(5)
	v_mfma_f32_32x32x16_bf16 v[34:49], v[144:147], v[70:73], v[34:49]
	s_waitcnt lgkmcnt(4)
	v_mfma_f32_32x32x16_bf16 v[50:65], v[148:151], v[70:73], v[50:65]
	ds_read_b128 v[168:171], v120 offset:128
	ds_read_b128 v[172:175], v120 offset:6784
	s_waitcnt lgkmcnt(5)
	v_mfma_f32_32x32x16_bf16 v[34:49], v[152:155], v[74:77], v[34:49]
	s_waitcnt lgkmcnt(4)
	v_mfma_f32_32x32x16_bf16 v[50:65], v[156:159], v[74:77], v[50:65]
	ds_read_b128 v[176:179], v120 offset:160
	ds_read_b128 v[180:183], v120 offset:6816
	s_waitcnt lgkmcnt(5)
	v_mfma_f32_32x32x16_bf16 v[34:49], v[160:163], v[78:81], v[34:49]
	s_waitcnt lgkmcnt(4)
	v_mfma_f32_32x32x16_bf16 v[50:65], v[164:167], v[78:81], v[50:65]
	s_waitcnt lgkmcnt(3)
	v_mfma_f32_32x32x16_bf16 v[34:49], v[168:171], v[106:109], v[34:49]
	s_waitcnt lgkmcnt(2)
	v_mfma_f32_32x32x16_bf16 v[50:65], v[172:175], v[106:109], v[50:65]
	s_waitcnt lgkmcnt(1)
	v_mfma_f32_32x32x16_bf16 v[34:49], v[176:179], v[110:113], v[34:49]
	s_waitcnt lgkmcnt(0)
	v_mfma_f32_32x32x16_bf16 v[50:65], v[180:183], v[110:113], v[50:65]
	s_nop 11
	v_max3_f32 v120, v34, v35, v36
	v_max3_f32 v120, v120, v37, v38
	v_max3_f32 v120, v120, v39, v40
	v_max3_f32 v120, v120, v41, v42
	v_max3_f32 v120, v120, v43, v44
	v_max3_f32 v120, v120, v45, v46
	v_max3_f32 v120, v120, v47, v48
	v_max3_f32 v120, v120, v49, v50
	v_max3_f32 v120, v120, v51, v52
	v_max3_f32 v120, v120, v53, v54
	v_max3_f32 v120, v120, v55, v56
	v_max3_f32 v120, v120, v57, v58
	v_max3_f32 v120, v120, v59, v60
	v_max3_f32 v120, v120, v61, v62
	v_max3_f32 v120, v120, v63, v64
	v_max_f32_e32 v120, v120, v65
	v_sub_f32_e32 v130, v236, v120
	v_cmp_gt_f32_e32 vcc, 0xc2200000, v130
	s_cbranch_vccnz .Llazy8_full
	ds_read_b64_tr_b16 v[136:137], v184 offset:13312
	ds_read_b64_tr_b16 v[138:139], v184 offset:14464
	ds_read_b64_tr_b16 v[140:141], v184 offset:13376
	ds_read_b64_tr_b16 v[142:143], v184 offset:14528
	ds_read_b64_tr_b16 v[144:145], v184 offset:15616
	ds_read_b64_tr_b16 v[146:147], v184 offset:16768
	ds_read_b64_tr_b16 v[148:149], v184 offset:15680
	ds_read_b64_tr_b16 v[150:151], v184 offset:16832
	ds_read_b64_tr_b16 v[152:153], v184 offset:17920
	ds_read_b64_tr_b16 v[154:155], v184 offset:19072
	ds_read_b64_tr_b16 v[156:157], v184 offset:17984
	ds_read_b64_tr_b16 v[158:159], v184 offset:19136
	ds_read_b64_tr_b16 v[160:161], v184 offset:20224
	ds_read_b64_tr_b16 v[162:163], v184 offset:21376
	ds_read_b64_tr_b16 v[164:165], v184 offset:20288
	ds_read_b64_tr_b16 v[166:167], v184 offset:21440
	v_mov_b32_e32 v130, v129
	v_mov_b32_e32 v120, 1.0
	s_branch .LBB0_1168

.LBB0_1179:
	s_cmp_ge_u32 s42, s66
	s_cselect_b64 s[48:49], -1, 0
	s_cmp_ge_i32 s44, s39
	s_cselect_b64 s[50:51], -1, 0
	s_or_b64 s[48:49], s[50:51], s[48:49]
	s_and_b64 vcc, exec, s[48:49]
	s_cbranch_vccnz .LBB0_1184
	v_add_u32_e32 v120, v124, v198
	ds_read_b128 v[136:139], v120 offset:32768
	ds_read_b128 v[140:143], v120 offset:39424
	ds_read_b128 v[144:147], v120 offset:32800
	ds_read_b128 v[148:151], v120 offset:39456
	ds_read_b128 v[152:155], v120 offset:32832
	ds_read_b128 v[156:159], v120 offset:39488
	v_add_u32_e32 v184, v125, v126
	s_waitcnt lgkmcnt(5)
	v_mfma_f32_32x32x16_bf16 v[34:49], v[136:139], v[66:69], v[220:235]
	s_waitcnt lgkmcnt(4)
	v_mfma_f32_32x32x16_bf16 v[50:65], v[140:143], v[66:69], v[220:235]
	ds_read_b128 v[160:163], v120 offset:32864
	ds_read_b128 v[164:167], v120 offset:39520
	s_waitcnt lgkmcnt(5)
	v_mfma_f32_32x32x16_bf16 v[34:49], v[144:147], v[70:73], v[34:49]
	s_waitcnt lgkmcnt(4)
	v_mfma_f32_32x32x16_bf16 v[50:65], v[148:151], v[70:73], v[50:65]
	ds_read_b128 v[168:171], v120 offset:32896
	ds_read_b128 v[172:175], v120 offset:39552
	s_waitcnt lgkmcnt(5)
	v_mfma_f32_32x32x16_bf16 v[34:49], v[152:155], v[74:77], v[34:49]
	s_waitcnt lgkmcnt(4)
	v_mfma_f32_32x32x16_bf16 v[50:65], v[156:159], v[74:77], v[50:65]
	ds_read_b128 v[176:179], v120 offset:32928
	ds_read_b128 v[180:183], v120 offset:39584
	s_waitcnt lgkmcnt(5)
	v_mfma_f32_32x32x16_bf16 v[34:49], v[160:163], v[78:81], v[34:49]
	s_waitcnt lgkmcnt(4)
	v_mfma_f32_32x32x16_bf16 v[50:65], v[164:167], v[78:81], v[50:65]
	s_waitcnt lgkmcnt(3)
	v_mfma_f32_32x32x16_bf16 v[34:49], v[168:171], v[106:109], v[34:49]
	s_waitcnt lgkmcnt(2)
	v_mfma_f32_32x32x16_bf16 v[50:65], v[172:175], v[106:109], v[50:65]
	s_waitcnt lgkmcnt(1)
	v_mfma_f32_32x32x16_bf16 v[34:49], v[176:179], v[110:113], v[34:49]
	s_waitcnt lgkmcnt(0)
	v_mfma_f32_32x32x16_bf16 v[50:65], v[180:183], v[110:113], v[50:65]
	s_nop 11
	v_max3_f32 v120, v34, v35, v36
	v_max3_f32 v120, v120, v37, v38
	v_max3_f32 v120, v120, v39, v40
	v_max3_f32 v120, v120, v41, v42
	v_max3_f32 v120, v120, v43, v44
	v_max3_f32 v120, v120, v45, v46
	v_max3_f32 v120, v120, v47, v48
	v_max3_f32 v120, v120, v49, v50
	v_max3_f32 v120, v120, v51, v52
	v_max3_f32 v120, v120, v53, v54
	v_max3_f32 v120, v120, v55, v56
	v_max3_f32 v120, v120, v57, v58
	v_max3_f32 v120, v120, v59, v60
	v_max3_f32 v120, v120, v61, v62
	v_max3_f32 v120, v120, v63, v64
	v_max_f32_e32 v120, v120, v65
	v_sub_f32_e32 v129, v236, v120
	v_cmp_gt_f32_e32 vcc, 0xc2200000, v129
	s_cbranch_vccnz .Llazy9_full
	ds_read_b64_tr_b16 v[136:137], v184 offset:46080
	ds_read_b64_tr_b16 v[138:139], v184 offset:47232
	ds_read_b64_tr_b16 v[140:141], v184 offset:46144
	ds_read_b64_tr_b16 v[142:143], v184 offset:47296
	ds_read_b64_tr_b16 v[144:145], v184 offset:48384
	ds_read_b64_tr_b16 v[146:147], v184 offset:49536
	ds_read_b64_tr_b16 v[148:149], v184 offset:48448
	ds_read_b64_tr_b16 v[150:151], v184 offset:49600
	ds_read_b64_tr_b16 v[152:153], v184 offset:50688
	ds_read_b64_tr_b16 v[154:155], v184 offset:51840
	ds_read_b64_tr_b16 v[156:157], v184 offset:50752
	ds_read_b64_tr_b16 v[158:159], v184 offset:51904
	ds_read_b64_tr_b16 v[160:161], v184 offset:52992
	ds_read_b64_tr_b16 v[162:163], v184 offset:54144
	ds_read_b64_tr_b16 v[164:165], v184 offset:53056
	ds_read_b64_tr_b16 v[166:167], v184 offset:54208
	v_mov_b32_e32 v129, v130
	v_mov_b32_e32 v120, 1.0
	s_branch .LBB0_1182
